# PP row loads of the freshly written in-proj output without the nt hint (gel-loop nt loads kept)
# baseline (speedup 1.0000x reference)
.LBB0_1591:
	s_movk_i32 s6, 0x1fff
	v_cmp_lt_i32_e64 s[50:51], s6, v28
	v_cmp_gt_i32_e64 s[52:53], s33, v28
	s_and_saveexec_b64 s[6:7], s[52:53]
	s_xor_b64 s[6:7], exec, s[6:7]
	v_ashrrev_i32_e32 v29, 8, v28
	v_and_b32_e32 v128, 0xff, v28
	s_or_saveexec_b64 s[6:7], s[6:7]
	v_mov_b32_e32 v80, v28
	s_xor_b64 exec, exec, s[6:7]
	v_add_u32_e32 v0, 0xffffe000, v28
	v_lshrrev_b32_e32 v29, 10, v0
	v_and_b32_e32 v128, 0x3ff, v28
	v_mul_u32_u24_e32 v0, 0x600, v29
	s_movk_i32 s8, 0x2200
	v_add3_u32 v80, v128, v0, s8
	s_or_b64 exec, exec, s[6:7]
	v_lshl_add_u64 v[4:5], v[76:77], 0, v[44:45]
	global_load_dwordx2 v[20:21], v[4:5], off offset:-2048
	global_load_dwordx2 v[22:23], v[4:5], off offset:-1536
	global_load_dwordx2 v[114:115], v[4:5], off offset:-1024
	global_load_dwordx2 v[112:113], v[4:5], off offset:-512
	v_mov_b32_e32 v24, 0
	v_mov_b32_e32 v100, 0
	v_mov_b32_e32 v101, 0
	v_mov_b32_e32 v102, 0
	v_mov_b32_e32 v103, 0
	s_and_saveexec_b64 s[6:7], s[0:1]
	s_cbranch_execz .LBB0_1597
	global_load_dwordx2 v[0:1], v[4:5], off
	s_waitcnt vmcnt(0)
	v_lshlrev_b32_e32 v100, 16, v0
	v_and_b32_e32 v101, 0xffff0000, v0
	v_lshlrev_b32_e32 v102, 16, v1
	v_and_b32_e32 v103, 0xffff0000, v1
.LBB0_1597:
	s_or_b64 exec, exec, s[6:7]
	v_mov_b32_e32 v25, 0
	v_mov_b32_e32 v26, 0
	v_mov_b32_e32 v27, 0
	s_and_saveexec_b64 s[6:7], s[0:1]
	s_cbranch_execz .LBB0_1599
	global_load_dwordx2 v[0:1], v[4:5], off offset:256
	s_waitcnt vmcnt(0)
	v_lshlrev_b32_e32 v24, 16, v0
	v_and_b32_e32 v25, 0xffff0000, v0
	v_lshlrev_b32_e32 v26, 16, v1
	v_and_b32_e32 v27, 0xffff0000, v1
.LBB0_1599:
	s_or_b64 exec, exec, s[6:7]
	v_mov_b32_e32 v82, 0
	v_mov_b32_e32 v88, 0
	v_mov_b32_e32 v89, 0
	v_mov_b32_e32 v90, 0
	v_mov_b32_e32 v91, 0
	s_and_saveexec_b64 s[6:7], s[38:39]
	s_cbranch_execz .LBB0_1601
	global_load_dwordx2 v[0:1], v[4:5], off offset:1024
	s_waitcnt vmcnt(0)
	v_lshlrev_b32_e32 v88, 16, v0
	v_and_b32_e32 v89, 0xffff0000, v0
	v_lshlrev_b32_e32 v90, 16, v1
	v_and_b32_e32 v91, 0xffff0000, v1
.LBB0_1601:
	s_or_b64 exec, exec, s[6:7]
	v_mov_b32_e32 v83, 0
	v_mov_b32_e32 v84, 0
	v_mov_b32_e32 v85, 0
	s_and_saveexec_b64 s[6:7], s[0:1]
	s_cbranch_execz .LBB0_1603
	global_load_dwordx2 v[0:1], v[4:5], off offset:1408
	s_waitcnt vmcnt(0)
	v_lshlrev_b32_e32 v82, 16, v0
	v_and_b32_e32 v83, 0xffff0000, v0
	v_lshlrev_b32_e32 v84, 16, v1
	v_and_b32_e32 v85, 0xffff0000, v1
.LBB0_1603:
	s_or_b64 exec, exec, s[6:7]
	v_mov_b32_e32 v8, 0
	v_mov_b32_e32 v0, 0
	v_mov_b32_e32 v1, 0
	v_mov_b32_e32 v2, 0
	v_mov_b32_e32 v3, 0
	s_and_saveexec_b64 s[6:7], s[36:37]
	s_cbranch_execz .LBB0_1605
	global_load_dwordx2 v[2:3], v[4:5], off offset:1664
	s_waitcnt vmcnt(0)
	v_lshlrev_b32_e32 v0, 16, v2
	v_and_b32_e32 v1, 0xffff0000, v2
	v_lshlrev_b32_e32 v2, 16, v3
	v_and_b32_e32 v3, 0xffff0000, v3
